# P1 and P4 GEMM units start without the 128 accumulator v_movs: phases 1-2 of the first k iteration run from a peeled copy whose first MFMA per tuple takes C=0
# speedup vs baseline: 1.0031x; 1.0031x over previous
.LBB0_145:
	s_add_u32 s27, s50, 0x100
	s_addc_u32 s56, s51, 0
	s_mov_b32 s57, -2
	s_waitcnt lgkmcnt(0)
	ds_read_b128 v[128:131], v188
	ds_read_b128 v[132:135], v188 offset:1024
	ds_read_b128 v[136:139], v188 offset:2048
	ds_read_b128 v[140:143], v188 offset:3072
	ds_read_b128 v[144:147], v189
	ds_read_b128 v[148:151], v189 offset:1024
	ds_read_b128 v[176:179], v189 offset:2048
	ds_read_b128 v[180:183], v189 offset:3072
	s_add_u32 s50, s48, 0x100
	s_addc_u32 s51, s49, 0
	s_cmp_eq_u32 s57, 28
	s_cselect_b32 s55, s21, s51
	s_cselect_b32 s54, s20, s50
	s_cselect_b32 s53, s23, s56
	s_cselect_b32 s52, s22, s27
	v_lshl_add_u64 v[184:185], s[48:49], 0, v[170:171]
	s_add_i32 m0, s60, 0xc000
	ds_read_b128 v[194:197], v190
	ds_read_b128 v[198:201], v190 offset:1024
	ds_read_b128 v[202:205], v190 offset:2048
	ds_read_b128 v[206:209], v190 offset:3072
	ds_read_b128 v[210:213], v190 offset:4096
	ds_read_b128 v[214:217], v190 offset:5120
	ds_read_b128 v[218:221], v190 offset:6144
	ds_read_b128 v[222:225], v190 offset:7168
	global_load_lds_dwordx4 v[184:185], off
	v_lshl_add_u64 v[184:185], s[48:49], 0, v[172:173]
	s_add_i32 m0, s60, 0xe000
	s_nop 0
	global_load_lds_dwordx4 v[184:185], off
	s_waitcnt vmcnt(8)
	s_waitcnt lgkmcnt(0)
	s_barrier
	s_setprio 1
	s_waitcnt lgkmcnt(0)
	v_mfma_f32_16x16x32_bf16 v[120:123], v[128:131], v[194:197], 0
	v_mfma_f32_16x16x32_bf16 v[124:127], v[136:139], v[194:197], 0
	v_mfma_f32_16x16x32_bf16 v[108:111], v[128:131], v[202:205], 0
	v_mfma_f32_16x16x32_bf16 v[104:107], v[136:139], v[202:205], 0
	v_mfma_f32_16x16x32_bf16 v[92:95], v[128:131], v[210:213], 0
	v_mfma_f32_16x16x32_bf16 v[88:91], v[136:139], v[210:213], 0
	v_mfma_f32_16x16x32_bf16 v[76:79], v[128:131], v[218:221], 0
	v_mfma_f32_16x16x32_bf16 v[72:75], v[136:139], v[218:221], 0
	v_mfma_f32_16x16x32_bf16 v[120:123], v[132:135], v[198:201], v[120:123]
	v_mfma_f32_16x16x32_bf16 v[124:127], v[140:143], v[198:201], v[124:127]
	v_mfma_f32_16x16x32_bf16 v[108:111], v[132:135], v[206:209], v[108:111]
	v_mfma_f32_16x16x32_bf16 v[104:107], v[140:143], v[206:209], v[104:107]
	v_mfma_f32_16x16x32_bf16 v[92:95], v[132:135], v[214:217], v[92:95]
	v_mfma_f32_16x16x32_bf16 v[88:91], v[140:143], v[214:217], v[88:91]
	v_mfma_f32_16x16x32_bf16 v[76:79], v[132:135], v[222:225], v[76:79]
	v_mfma_f32_16x16x32_bf16 v[72:75], v[140:143], v[222:225], v[72:75]
	s_setprio 0
	s_setprio 1
	v_mfma_f32_16x16x32_bf16 v[112:115], v[144:147], v[194:197], 0
	v_mfma_f32_16x16x32_bf16 v[116:119], v[176:179], v[194:197], 0
	v_mfma_f32_16x16x32_bf16 v[100:103], v[144:147], v[202:205], 0
	v_mfma_f32_16x16x32_bf16 v[96:99], v[176:179], v[202:205], 0
	v_mfma_f32_16x16x32_bf16 v[84:87], v[144:147], v[210:213], 0
	v_mfma_f32_16x16x32_bf16 v[80:83], v[176:179], v[210:213], 0
	v_mfma_f32_16x16x32_bf16 v[68:71], v[144:147], v[218:221], 0
	v_mfma_f32_16x16x32_bf16 v[64:67], v[176:179], v[218:221], 0
	v_mfma_f32_16x16x32_bf16 v[112:115], v[148:151], v[198:201], v[112:115]
	v_mfma_f32_16x16x32_bf16 v[116:119], v[180:183], v[198:201], v[116:119]
	v_mfma_f32_16x16x32_bf16 v[100:103], v[148:151], v[206:209], v[100:103]
	v_mfma_f32_16x16x32_bf16 v[96:99], v[180:183], v[206:209], v[96:99]
	v_mfma_f32_16x16x32_bf16 v[84:87], v[148:151], v[214:217], v[84:87]
	v_mfma_f32_16x16x32_bf16 v[80:83], v[180:183], v[214:217], v[80:83]
	v_mfma_f32_16x16x32_bf16 v[68:71], v[148:151], v[222:225], v[68:71]
	v_mfma_f32_16x16x32_bf16 v[64:67], v[180:183], v[222:225], v[64:67]
	s_setprio 0
	s_barrier
	s_add_i32 s48, s71, s3
	v_lshl_add_u64 v[184:185], s[52:53], 0, v[154:155]
	s_mov_b32 m0, s48
	ds_read_b128 v[194:197], v190 offset:16384
	ds_read_b128 v[198:201], v190 offset:17408
	ds_read_b128 v[202:205], v190 offset:18432
	ds_read_b128 v[206:209], v190 offset:19456
	ds_read_b128 v[210:213], v190 offset:20480
	ds_read_b128 v[214:217], v190 offset:21504
	ds_read_b128 v[218:221], v190 offset:22528
	ds_read_b128 v[222:225], v190 offset:23552
	global_load_lds_dwordx4 v[184:185], off
	s_add_i32 m0, s48, 0x2000
	s_add_u32 s48, s52, 0x80000
	v_lshl_add_u64 v[226:227], s[52:53], 0, v[158:159]
	s_addc_u32 s49, s53, 0
	s_add_i32 s58, s72, s3
	global_load_lds_dwordx4 v[226:227], off
	v_lshl_add_u64 v[228:229], s[48:49], 0, v[154:155]
	s_mov_b32 m0, s58
	v_lshl_add_u64 v[230:231], s[54:55], 0, v[156:157]
	global_load_lds_dwordx4 v[228:229], off
	v_lshl_add_u64 v[228:229], s[48:49], 0, v[158:159]
	s_add_i32 m0, s58, 0x2000
	s_nop 0
	global_load_lds_dwordx4 v[228:229], off
	v_lshl_add_u64 v[228:229], s[54:55], 0, v[152:153]
	s_mov_b32 m0, s60
	s_nop 0
	global_load_lds_dwordx4 v[228:229], off
	s_mov_b32 m0, s61
	s_nop 0
	global_load_lds_dwordx4 v[230:231], off
	s_waitcnt vmcnt(8)
	s_waitcnt lgkmcnt(0)
	s_barrier
	s_setprio 1
	s_waitcnt lgkmcnt(0)
	v_mfma_f32_16x16x32_bf16 v[60:63], v[128:131], v[194:197], 0
	v_mfma_f32_16x16x32_bf16 v[56:59], v[136:139], v[194:197], 0
	v_mfma_f32_16x16x32_bf16 v[44:47], v[128:131], v[202:205], 0
	v_mfma_f32_16x16x32_bf16 v[40:43], v[136:139], v[202:205], 0
	v_mfma_f32_16x16x32_bf16 v[28:31], v[128:131], v[210:213], 0
	v_mfma_f32_16x16x32_bf16 v[24:27], v[136:139], v[210:213], 0
	v_mfma_f32_16x16x32_bf16 v[12:15], v[128:131], v[218:221], 0
	v_mfma_f32_16x16x32_bf16 v[8:11], v[136:139], v[218:221], 0
	v_mfma_f32_16x16x32_bf16 v[60:63], v[132:135], v[198:201], v[60:63]
	v_mfma_f32_16x16x32_bf16 v[56:59], v[140:143], v[198:201], v[56:59]
	v_mfma_f32_16x16x32_bf16 v[44:47], v[132:135], v[206:209], v[44:47]
	v_mfma_f32_16x16x32_bf16 v[40:43], v[140:143], v[206:209], v[40:43]
	v_mfma_f32_16x16x32_bf16 v[28:31], v[132:135], v[214:217], v[28:31]
	v_mfma_f32_16x16x32_bf16 v[24:27], v[140:143], v[214:217], v[24:27]
	v_mfma_f32_16x16x32_bf16 v[12:15], v[132:135], v[222:225], v[12:15]
	v_mfma_f32_16x16x32_bf16 v[8:11], v[140:143], v[222:225], v[8:11]
	s_setprio 0
	s_setprio 1
	v_mfma_f32_16x16x32_bf16 v[52:55], v[144:147], v[194:197], 0
	v_mfma_f32_16x16x32_bf16 v[48:51], v[176:179], v[194:197], 0
	v_mfma_f32_16x16x32_bf16 v[36:39], v[144:147], v[202:205], 0
	v_mfma_f32_16x16x32_bf16 v[32:35], v[176:179], v[202:205], 0
	v_mfma_f32_16x16x32_bf16 v[20:23], v[144:147], v[210:213], 0
	v_mfma_f32_16x16x32_bf16 v[16:19], v[176:179], v[210:213], 0
	v_mfma_f32_16x16x32_bf16 v[4:7], v[144:147], v[218:221], 0
	v_mfma_f32_16x16x32_bf16 v[0:3], v[176:179], v[218:221], 0
	v_mfma_f32_16x16x32_bf16 v[52:55], v[148:151], v[198:201], v[52:55]
	v_mfma_f32_16x16x32_bf16 v[48:51], v[180:183], v[198:201], v[48:51]
	v_mfma_f32_16x16x32_bf16 v[36:39], v[148:151], v[206:209], v[36:39]
	v_mfma_f32_16x16x32_bf16 v[32:35], v[180:183], v[206:209], v[32:35]
	v_mfma_f32_16x16x32_bf16 v[20:23], v[148:151], v[214:217], v[20:23]
	v_mfma_f32_16x16x32_bf16 v[16:19], v[180:183], v[214:217], v[16:19]
	v_mfma_f32_16x16x32_bf16 v[4:7], v[148:151], v[222:225], v[4:7]
	v_mfma_f32_16x16x32_bf16 v[0:3], v[180:183], v[222:225], v[0:3]
	s_setprio 0
	s_barrier
	s_branch .Lpeel_mid_p1

.Lpeel_mid_p1:
	s_add_i32 s58, 0, 0x18000
	s_add_i32 s59, 0, 0x1c000
	v_add_u32_e32 v140, s58, v186
	v_add_u32_e32 v160, s59, v186
	ds_read_b128 v[128:131], v140
	ds_read_b128 v[132:135], v140 offset:1024
	ds_read_b128 v[136:139], v140 offset:2048
	ds_read_b128 v[140:143], v140 offset:3072
	ds_read_b128 v[144:147], v160
	ds_read_b128 v[148:151], v160 offset:1024
	ds_read_b128 v[176:179], v160 offset:2048
	ds_read_b128 v[180:183], v160 offset:3072
	s_add_u32 s48, s54, 0xa0000
	s_addc_u32 s49, s55, 0
	s_mov_b32 m0, s62
	v_lshl_add_u64 v[232:233], s[48:49], 0, v[152:153]
	ds_read_b128 v[194:197], v190 offset:32768
	ds_read_b128 v[198:201], v190 offset:33792
	ds_read_b128 v[202:205], v190 offset:34816
	ds_read_b128 v[206:209], v190 offset:35840
	ds_read_b128 v[210:213], v190 offset:36864
	ds_read_b128 v[214:217], v190 offset:37888
	ds_read_b128 v[218:221], v190 offset:38912
	ds_read_b128 v[222:225], v190 offset:39936
	global_load_lds_dwordx4 v[232:233], off
	v_lshl_add_u64 v[232:233], s[48:49], 0, v[156:157]
	s_mov_b32 m0, s63
	s_nop 0
	global_load_lds_dwordx4 v[232:233], off
	s_waitcnt vmcnt(8)
	s_waitcnt lgkmcnt(0)
	s_barrier
	s_setprio 1
	s_waitcnt lgkmcnt(0)
	v_mfma_f32_16x16x32_bf16 v[120:123], v[128:131], v[194:197], v[120:123]
	v_mfma_f32_16x16x32_bf16 v[124:127], v[136:139], v[194:197], v[124:127]
	v_mfma_f32_16x16x32_bf16 v[108:111], v[128:131], v[202:205], v[108:111]
	v_mfma_f32_16x16x32_bf16 v[104:107], v[136:139], v[202:205], v[104:107]
	v_mfma_f32_16x16x32_bf16 v[92:95], v[128:131], v[210:213], v[92:95]
	v_mfma_f32_16x16x32_bf16 v[88:91], v[136:139], v[210:213], v[88:91]
	v_mfma_f32_16x16x32_bf16 v[76:79], v[128:131], v[218:221], v[76:79]
	v_mfma_f32_16x16x32_bf16 v[72:75], v[136:139], v[218:221], v[72:75]
	v_mfma_f32_16x16x32_bf16 v[120:123], v[132:135], v[198:201], v[120:123]
	v_mfma_f32_16x16x32_bf16 v[124:127], v[140:143], v[198:201], v[124:127]
	v_mfma_f32_16x16x32_bf16 v[108:111], v[132:135], v[206:209], v[108:111]
	v_mfma_f32_16x16x32_bf16 v[104:107], v[140:143], v[206:209], v[104:107]
	v_mfma_f32_16x16x32_bf16 v[92:95], v[132:135], v[214:217], v[92:95]
	v_mfma_f32_16x16x32_bf16 v[88:91], v[140:143], v[214:217], v[88:91]
	v_mfma_f32_16x16x32_bf16 v[76:79], v[132:135], v[222:225], v[76:79]
	v_mfma_f32_16x16x32_bf16 v[72:75], v[140:143], v[222:225], v[72:75]
	s_setprio 0
	s_setprio 1
	v_mfma_f32_16x16x32_bf16 v[112:115], v[144:147], v[194:197], v[112:115]
	v_mfma_f32_16x16x32_bf16 v[116:119], v[176:179], v[194:197], v[116:119]
	v_mfma_f32_16x16x32_bf16 v[100:103], v[144:147], v[202:205], v[100:103]
	v_mfma_f32_16x16x32_bf16 v[96:99], v[176:179], v[202:205], v[96:99]
	v_mfma_f32_16x16x32_bf16 v[84:87], v[144:147], v[210:213], v[84:87]
	v_mfma_f32_16x16x32_bf16 v[80:83], v[176:179], v[210:213], v[80:83]
	v_mfma_f32_16x16x32_bf16 v[68:71], v[144:147], v[218:221], v[68:71]
	v_mfma_f32_16x16x32_bf16 v[64:67], v[176:179], v[218:221], v[64:67]
	v_mfma_f32_16x16x32_bf16 v[112:115], v[148:151], v[198:201], v[112:115]
	v_mfma_f32_16x16x32_bf16 v[116:119], v[180:183], v[198:201], v[116:119]
	v_mfma_f32_16x16x32_bf16 v[100:103], v[148:151], v[206:209], v[100:103]
	v_mfma_f32_16x16x32_bf16 v[96:99], v[180:183], v[206:209], v[96:99]
	v_mfma_f32_16x16x32_bf16 v[84:87], v[148:151], v[214:217], v[84:87]
	v_mfma_f32_16x16x32_bf16 v[80:83], v[180:183], v[214:217], v[80:83]
	v_mfma_f32_16x16x32_bf16 v[68:71], v[148:151], v[222:225], v[68:71]
	v_mfma_f32_16x16x32_bf16 v[64:67], v[180:183], v[222:225], v[64:67]
	s_setprio 0
	s_barrier
	s_add_i32 s48, s58, s3
	v_lshl_add_u64 v[184:185], v[184:185], 0, s[14:15]
	s_mov_b32 m0, s48
	ds_read_b128 v[194:197], v190 offset:49152
	ds_read_b128 v[198:201], v190 offset:50176
	ds_read_b128 v[202:205], v190 offset:51200
	ds_read_b128 v[206:209], v190 offset:52224
	ds_read_b128 v[210:213], v190 offset:53248
	ds_read_b128 v[214:217], v190 offset:54272
	ds_read_b128 v[218:221], v190 offset:55296
	ds_read_b128 v[222:225], v190 offset:56320
	global_load_lds_dwordx4 v[184:185], off
	s_add_i32 m0, s48, 0x2000
	s_add_u32 s48, s52, 0x80080
	v_lshl_add_u64 v[184:185], v[226:227], 0, s[14:15]
	s_addc_u32 s49, s53, 0
	s_add_i32 s52, s59, s3
	global_load_lds_dwordx4 v[184:185], off
	v_lshl_add_u64 v[184:185], s[48:49], 0, v[154:155]
	s_mov_b32 m0, s52
	s_nop 0
	global_load_lds_dwordx4 v[184:185], off
	v_lshl_add_u64 v[184:185], s[48:49], 0, v[158:159]
	s_add_i32 m0, s52, 0x2000
	s_nop 0
	global_load_lds_dwordx4 v[184:185], off
	v_lshl_add_u64 v[184:185], v[228:229], 0, s[14:15]
	s_mov_b32 m0, s66
	s_nop 0
	global_load_lds_dwordx4 v[184:185], off
	v_lshl_add_u64 v[184:185], v[230:231], 0, s[14:15]
	s_mov_b32 m0, s67
	s_nop 0
	global_load_lds_dwordx4 v[184:185], off
	s_waitcnt vmcnt(8)
	s_waitcnt lgkmcnt(0)
	s_barrier
	s_setprio 1
	s_waitcnt lgkmcnt(0)
	v_mfma_f32_16x16x32_bf16 v[60:63], v[128:131], v[194:197], v[60:63]
	v_mfma_f32_16x16x32_bf16 v[56:59], v[136:139], v[194:197], v[56:59]
	v_mfma_f32_16x16x32_bf16 v[44:47], v[128:131], v[202:205], v[44:47]
	v_mfma_f32_16x16x32_bf16 v[40:43], v[136:139], v[202:205], v[40:43]
	v_mfma_f32_16x16x32_bf16 v[28:31], v[128:131], v[210:213], v[28:31]
	v_mfma_f32_16x16x32_bf16 v[24:27], v[136:139], v[210:213], v[24:27]
	v_mfma_f32_16x16x32_bf16 v[12:15], v[128:131], v[218:221], v[12:15]
	v_mfma_f32_16x16x32_bf16 v[8:11], v[136:139], v[218:221], v[8:11]
	v_mfma_f32_16x16x32_bf16 v[60:63], v[132:135], v[198:201], v[60:63]
	v_mfma_f32_16x16x32_bf16 v[56:59], v[140:143], v[198:201], v[56:59]
	v_mfma_f32_16x16x32_bf16 v[44:47], v[132:135], v[206:209], v[44:47]
	v_mfma_f32_16x16x32_bf16 v[40:43], v[140:143], v[206:209], v[40:43]
	v_mfma_f32_16x16x32_bf16 v[28:31], v[132:135], v[214:217], v[28:31]
	v_mfma_f32_16x16x32_bf16 v[24:27], v[140:143], v[214:217], v[24:27]
	v_mfma_f32_16x16x32_bf16 v[12:15], v[132:135], v[222:225], v[12:15]
	v_mfma_f32_16x16x32_bf16 v[8:11], v[140:143], v[222:225], v[8:11]
	s_setprio 0
	s_setprio 1
	v_mfma_f32_16x16x32_bf16 v[52:55], v[144:147], v[194:197], v[52:55]
	v_mfma_f32_16x16x32_bf16 v[48:51], v[176:179], v[194:197], v[48:51]
	v_mfma_f32_16x16x32_bf16 v[36:39], v[144:147], v[202:205], v[36:39]
	v_mfma_f32_16x16x32_bf16 v[32:35], v[176:179], v[202:205], v[32:35]
	v_mfma_f32_16x16x32_bf16 v[20:23], v[144:147], v[210:213], v[20:23]
	v_mfma_f32_16x16x32_bf16 v[16:19], v[176:179], v[210:213], v[16:19]
	v_mfma_f32_16x16x32_bf16 v[4:7], v[144:147], v[218:221], v[4:7]
	v_mfma_f32_16x16x32_bf16 v[0:3], v[176:179], v[218:221], v[0:3]
	v_mfma_f32_16x16x32_bf16 v[52:55], v[148:151], v[198:201], v[52:55]
	v_mfma_f32_16x16x32_bf16 v[48:51], v[180:183], v[198:201], v[48:51]
	v_mfma_f32_16x16x32_bf16 v[36:39], v[148:151], v[206:209], v[36:39]
	v_mfma_f32_16x16x32_bf16 v[32:35], v[180:183], v[206:209], v[32:35]
	v_mfma_f32_16x16x32_bf16 v[20:23], v[148:151], v[214:217], v[20:23]
	v_mfma_f32_16x16x32_bf16 v[16:19], v[180:183], v[214:217], v[16:19]
	v_mfma_f32_16x16x32_bf16 v[4:7], v[148:151], v[222:225], v[4:7]
	v_mfma_f32_16x16x32_bf16 v[0:3], v[180:183], v[222:225], v[0:3]
	s_setprio 0
	s_barrier
	s_add_i32 s57, s57, 2
	s_add_u32 s27, s27, 0x100
	s_addc_u32 s56, s56, 0
	s_cmp_gt_u32 s57, 29
	s_mov_b64 s[48:49], s[50:51]
	s_cbranch_scc0 .LBB0_146
	s_and_b64 vcc, exec, s[18:19]
	s_cbranch_vccz .LBB0_149
	s_barrier

.LBB0_671:
	s_add_u32 s6, s6, 0x80080
	s_addc_u32 s7, s7, 0
	s_add_u32 s5, s40, 0x100
	s_addc_u32 s25, s41, 0
	s_mov_b32 s56, -2
	ds_read_b128 v[128:131], v185
	ds_read_b128 v[132:135], v185 offset:1024
	ds_read_b128 v[136:139], v185 offset:2048
	ds_read_b128 v[140:143], v185 offset:3072
	ds_read_b128 v[162:165], v186
	ds_read_b128 v[166:169], v186 offset:1024
	ds_read_b128 v[170:173], v186 offset:2048
	ds_read_b128 v[174:177], v186 offset:3072
	s_add_u32 s38, s6, 0xfff80080
	s_addc_u32 s39, s7, -1
	s_cmp_eq_u32 s56, 28
	s_cselect_b32 s41, s27, s39
	s_cselect_b32 s40, s26, s38
	s_cselect_b32 s39, s23, s25
	s_cselect_b32 s38, s22, s5
	v_lshl_add_u64 v[182:183], s[6:7], 0, v[158:159]
	s_add_i32 m0, s42, 0xc000
	ds_read_b128 v[178:181], v188
	ds_read_b128 v[192:195], v188 offset:1024
	ds_read_b128 v[196:199], v188 offset:2048
	ds_read_b128 v[200:203], v188 offset:3072
	ds_read_b128 v[204:207], v188 offset:4096
	ds_read_b128 v[208:211], v188 offset:5120
	ds_read_b128 v[212:215], v188 offset:6144
	ds_read_b128 v[216:219], v188 offset:7168
	global_load_lds_dwordx4 v[182:183], off
	v_lshl_add_u64 v[182:183], s[6:7], 0, v[160:161]
	s_add_i32 m0, s42, 0xe000
	s_nop 0
	global_load_lds_dwordx4 v[182:183], off
	s_waitcnt vmcnt(8)
	s_waitcnt lgkmcnt(0)
	s_barrier
	s_setprio 1
	s_waitcnt lgkmcnt(0)
	v_mfma_f32_16x16x32_bf16 v[124:127], v[128:131], v[178:181], 0
	v_mfma_f32_16x16x32_bf16 v[120:123], v[136:139], v[178:181], 0
	v_mfma_f32_16x16x32_bf16 v[108:111], v[128:131], v[196:199], 0
	v_mfma_f32_16x16x32_bf16 v[104:107], v[136:139], v[196:199], 0
	v_mfma_f32_16x16x32_bf16 v[92:95], v[128:131], v[204:207], 0
	v_mfma_f32_16x16x32_bf16 v[88:91], v[136:139], v[204:207], 0
	v_mfma_f32_16x16x32_bf16 v[76:79], v[128:131], v[212:215], 0
	v_mfma_f32_16x16x32_bf16 v[72:75], v[136:139], v[212:215], 0
	v_mfma_f32_16x16x32_bf16 v[124:127], v[132:135], v[192:195], v[124:127]
	v_mfma_f32_16x16x32_bf16 v[120:123], v[140:143], v[192:195], v[120:123]
	v_mfma_f32_16x16x32_bf16 v[108:111], v[132:135], v[200:203], v[108:111]
	v_mfma_f32_16x16x32_bf16 v[104:107], v[140:143], v[200:203], v[104:107]
	v_mfma_f32_16x16x32_bf16 v[92:95], v[132:135], v[208:211], v[92:95]
	v_mfma_f32_16x16x32_bf16 v[88:91], v[140:143], v[208:211], v[88:91]
	v_mfma_f32_16x16x32_bf16 v[76:79], v[132:135], v[216:219], v[76:79]
	v_mfma_f32_16x16x32_bf16 v[72:75], v[140:143], v[216:219], v[72:75]
	s_setprio 0
	s_setprio 1
	v_mfma_f32_16x16x32_bf16 v[116:119], v[162:165], v[178:181], 0
	v_mfma_f32_16x16x32_bf16 v[112:115], v[170:173], v[178:181], 0
	v_mfma_f32_16x16x32_bf16 v[100:103], v[162:165], v[196:199], 0
	v_mfma_f32_16x16x32_bf16 v[96:99], v[170:173], v[196:199], 0
	v_mfma_f32_16x16x32_bf16 v[84:87], v[162:165], v[204:207], 0
	v_mfma_f32_16x16x32_bf16 v[80:83], v[170:173], v[204:207], 0
	v_mfma_f32_16x16x32_bf16 v[68:71], v[162:165], v[212:215], 0
	v_mfma_f32_16x16x32_bf16 v[64:67], v[170:173], v[212:215], 0
	v_mfma_f32_16x16x32_bf16 v[116:119], v[166:169], v[192:195], v[116:119]
	v_mfma_f32_16x16x32_bf16 v[112:115], v[174:177], v[192:195], v[112:115]
	v_mfma_f32_16x16x32_bf16 v[100:103], v[166:169], v[200:203], v[100:103]
	v_mfma_f32_16x16x32_bf16 v[96:99], v[174:177], v[200:203], v[96:99]
	v_mfma_f32_16x16x32_bf16 v[84:87], v[166:169], v[208:211], v[84:87]
	v_mfma_f32_16x16x32_bf16 v[80:83], v[174:177], v[208:211], v[80:83]
	v_mfma_f32_16x16x32_bf16 v[68:71], v[166:169], v[216:219], v[68:71]
	v_mfma_f32_16x16x32_bf16 v[64:67], v[174:177], v[216:219], v[64:67]
	s_setprio 0
	s_barrier
	s_add_i32 s57, s51, s35
	v_lshl_add_u64 v[182:183], s[38:39], 0, v[148:149]
	s_mov_b32 m0, s57
	ds_read_b128 v[178:181], v188 offset:16384
	ds_read_b128 v[192:195], v188 offset:17408
	ds_read_b128 v[196:199], v188 offset:18432
	ds_read_b128 v[200:203], v188 offset:19456
	ds_read_b128 v[204:207], v188 offset:20480
	ds_read_b128 v[208:211], v188 offset:21504
	ds_read_b128 v[212:215], v188 offset:22528
	ds_read_b128 v[216:219], v188 offset:23552
	global_load_lds_dwordx4 v[182:183], off
	s_add_i32 m0, s57, 0x2000
	s_add_u32 s58, s38, 0x80000
	v_lshl_add_u64 v[220:221], s[38:39], 0, v[144:145]
	s_addc_u32 s59, s39, 0
	s_add_i32 s57, s52, s35
	global_load_lds_dwordx4 v[220:221], off
	v_lshl_add_u64 v[222:223], s[58:59], 0, v[148:149]
	s_mov_b32 m0, s57
	v_lshl_add_u64 v[224:225], s[40:41], 0, v[146:147]
	global_load_lds_dwordx4 v[222:223], off
	v_lshl_add_u64 v[222:223], s[58:59], 0, v[144:145]
	s_add_i32 m0, s57, 0x2000
	s_nop 0
	global_load_lds_dwordx4 v[222:223], off
	v_lshl_add_u64 v[222:223], s[40:41], 0, v[150:151]
	s_mov_b32 m0, s42
	s_nop 0
	global_load_lds_dwordx4 v[222:223], off
	s_mov_b32 m0, s43
	s_nop 0
	global_load_lds_dwordx4 v[224:225], off
	s_waitcnt vmcnt(8)
	s_waitcnt lgkmcnt(0)
	s_barrier
	s_setprio 1
	s_waitcnt lgkmcnt(0)
	v_mfma_f32_16x16x32_bf16 v[60:63], v[128:131], v[178:181], 0
	v_mfma_f32_16x16x32_bf16 v[56:59], v[136:139], v[178:181], 0
	v_mfma_f32_16x16x32_bf16 v[44:47], v[128:131], v[196:199], 0
	v_mfma_f32_16x16x32_bf16 v[40:43], v[136:139], v[196:199], 0
	v_mfma_f32_16x16x32_bf16 v[28:31], v[128:131], v[204:207], 0
	v_mfma_f32_16x16x32_bf16 v[24:27], v[136:139], v[204:207], 0
	v_mfma_f32_16x16x32_bf16 v[12:15], v[128:131], v[212:215], 0
	v_mfma_f32_16x16x32_bf16 v[8:11], v[136:139], v[212:215], 0
	v_mfma_f32_16x16x32_bf16 v[60:63], v[132:135], v[192:195], v[60:63]
	v_mfma_f32_16x16x32_bf16 v[56:59], v[140:143], v[192:195], v[56:59]
	v_mfma_f32_16x16x32_bf16 v[44:47], v[132:135], v[200:203], v[44:47]
	v_mfma_f32_16x16x32_bf16 v[40:43], v[140:143], v[200:203], v[40:43]
	v_mfma_f32_16x16x32_bf16 v[28:31], v[132:135], v[208:211], v[28:31]
	v_mfma_f32_16x16x32_bf16 v[24:27], v[140:143], v[208:211], v[24:27]
	v_mfma_f32_16x16x32_bf16 v[12:15], v[132:135], v[216:219], v[12:15]
	v_mfma_f32_16x16x32_bf16 v[8:11], v[140:143], v[216:219], v[8:11]
	s_setprio 0
	s_setprio 1
	v_mfma_f32_16x16x32_bf16 v[52:55], v[162:165], v[178:181], 0
	v_mfma_f32_16x16x32_bf16 v[48:51], v[170:173], v[178:181], 0
	v_mfma_f32_16x16x32_bf16 v[36:39], v[162:165], v[196:199], 0
	v_mfma_f32_16x16x32_bf16 v[32:35], v[170:173], v[196:199], 0
	v_mfma_f32_16x16x32_bf16 v[20:23], v[162:165], v[204:207], 0
	v_mfma_f32_16x16x32_bf16 v[16:19], v[170:173], v[204:207], 0
	v_mfma_f32_16x16x32_bf16 v[4:7], v[162:165], v[212:215], 0
	v_mfma_f32_16x16x32_bf16 v[0:3], v[170:173], v[212:215], 0
	v_mfma_f32_16x16x32_bf16 v[52:55], v[166:169], v[192:195], v[52:55]
	v_mfma_f32_16x16x32_bf16 v[48:51], v[174:177], v[192:195], v[48:51]
	v_mfma_f32_16x16x32_bf16 v[36:39], v[166:169], v[200:203], v[36:39]
	v_mfma_f32_16x16x32_bf16 v[32:35], v[174:177], v[200:203], v[32:35]
	v_mfma_f32_16x16x32_bf16 v[20:23], v[166:169], v[208:211], v[20:23]
	v_mfma_f32_16x16x32_bf16 v[16:19], v[174:177], v[208:211], v[16:19]
	v_mfma_f32_16x16x32_bf16 v[4:7], v[166:169], v[216:219], v[4:7]
	v_mfma_f32_16x16x32_bf16 v[0:3], v[174:177], v[216:219], v[0:3]
	s_setprio 0
	s_barrier
	s_branch .Lpeel_mid_p4

.Lpeel_mid_p4:
	s_add_i32 s57, 0, 0x18000
	s_add_i32 s58, 0, 0x1c000
	v_add_u32_e32 v140, s57, v184
	v_add_u32_e32 v174, s58, v184
	ds_read_b128 v[128:131], v140
	ds_read_b128 v[132:135], v140 offset:1024
	ds_read_b128 v[136:139], v140 offset:2048
	ds_read_b128 v[140:143], v140 offset:3072
	ds_read_b128 v[162:165], v174
	ds_read_b128 v[166:169], v174 offset:1024
	ds_read_b128 v[170:173], v174 offset:2048
	ds_read_b128 v[174:177], v174 offset:3072
	s_add_u32 s40, s40, 0x80000
	s_addc_u32 s41, s41, 0
	s_mov_b32 m0, s44
	v_lshl_add_u64 v[226:227], s[40:41], 0, v[150:151]
	ds_read_b128 v[178:181], v188 offset:32768
	ds_read_b128 v[192:195], v188 offset:33792
	ds_read_b128 v[196:199], v188 offset:34816
	ds_read_b128 v[200:203], v188 offset:35840
	ds_read_b128 v[204:207], v188 offset:36864
	ds_read_b128 v[208:211], v188 offset:37888
	ds_read_b128 v[212:215], v188 offset:38912
	ds_read_b128 v[216:219], v188 offset:39936
	global_load_lds_dwordx4 v[226:227], off
	v_lshl_add_u64 v[226:227], s[40:41], 0, v[146:147]
	s_mov_b32 m0, s45
	s_nop 0
	global_load_lds_dwordx4 v[226:227], off
	s_waitcnt vmcnt(8)
	s_waitcnt lgkmcnt(0)
	s_barrier
	s_setprio 1
	s_waitcnt lgkmcnt(0)
	v_mfma_f32_16x16x32_bf16 v[124:127], v[128:131], v[178:181], v[124:127]
	v_mfma_f32_16x16x32_bf16 v[120:123], v[136:139], v[178:181], v[120:123]
	v_mfma_f32_16x16x32_bf16 v[108:111], v[128:131], v[196:199], v[108:111]
	v_mfma_f32_16x16x32_bf16 v[104:107], v[136:139], v[196:199], v[104:107]
	v_mfma_f32_16x16x32_bf16 v[92:95], v[128:131], v[204:207], v[92:95]
	v_mfma_f32_16x16x32_bf16 v[88:91], v[136:139], v[204:207], v[88:91]
	v_mfma_f32_16x16x32_bf16 v[76:79], v[128:131], v[212:215], v[76:79]
	v_mfma_f32_16x16x32_bf16 v[72:75], v[136:139], v[212:215], v[72:75]
	v_mfma_f32_16x16x32_bf16 v[124:127], v[132:135], v[192:195], v[124:127]
	v_mfma_f32_16x16x32_bf16 v[120:123], v[140:143], v[192:195], v[120:123]
	v_mfma_f32_16x16x32_bf16 v[108:111], v[132:135], v[200:203], v[108:111]
	v_mfma_f32_16x16x32_bf16 v[104:107], v[140:143], v[200:203], v[104:107]
	v_mfma_f32_16x16x32_bf16 v[92:95], v[132:135], v[208:211], v[92:95]
	v_mfma_f32_16x16x32_bf16 v[88:91], v[140:143], v[208:211], v[88:91]
	v_mfma_f32_16x16x32_bf16 v[76:79], v[132:135], v[216:219], v[76:79]
	v_mfma_f32_16x16x32_bf16 v[72:75], v[140:143], v[216:219], v[72:75]
	s_setprio 0
	s_setprio 1
	v_mfma_f32_16x16x32_bf16 v[116:119], v[162:165], v[178:181], v[116:119]
	v_mfma_f32_16x16x32_bf16 v[112:115], v[170:173], v[178:181], v[112:115]
	v_mfma_f32_16x16x32_bf16 v[100:103], v[162:165], v[196:199], v[100:103]
	v_mfma_f32_16x16x32_bf16 v[96:99], v[170:173], v[196:199], v[96:99]
	v_mfma_f32_16x16x32_bf16 v[84:87], v[162:165], v[204:207], v[84:87]
	v_mfma_f32_16x16x32_bf16 v[80:83], v[170:173], v[204:207], v[80:83]
	v_mfma_f32_16x16x32_bf16 v[68:71], v[162:165], v[212:215], v[68:71]
	v_mfma_f32_16x16x32_bf16 v[64:67], v[170:173], v[212:215], v[64:67]
	v_mfma_f32_16x16x32_bf16 v[116:119], v[166:169], v[192:195], v[116:119]
	v_mfma_f32_16x16x32_bf16 v[112:115], v[174:177], v[192:195], v[112:115]
	v_mfma_f32_16x16x32_bf16 v[100:103], v[166:169], v[200:203], v[100:103]
	v_mfma_f32_16x16x32_bf16 v[96:99], v[174:177], v[200:203], v[96:99]
	v_mfma_f32_16x16x32_bf16 v[84:87], v[166:169], v[208:211], v[84:87]
	v_mfma_f32_16x16x32_bf16 v[80:83], v[174:177], v[208:211], v[80:83]
	v_mfma_f32_16x16x32_bf16 v[68:71], v[166:169], v[216:219], v[68:71]
	v_mfma_f32_16x16x32_bf16 v[64:67], v[174:177], v[216:219], v[64:67]
	s_setprio 0
	s_barrier
	s_add_i32 s40, s57, s35
	v_lshl_add_u64 v[182:183], v[182:183], 0, s[14:15]
	s_mov_b32 m0, s40
	ds_read_b128 v[178:181], v188 offset:49152
	ds_read_b128 v[192:195], v188 offset:50176
	ds_read_b128 v[196:199], v188 offset:51200
	ds_read_b128 v[200:203], v188 offset:52224
	ds_read_b128 v[204:207], v188 offset:53248
	ds_read_b128 v[208:211], v188 offset:54272
	ds_read_b128 v[212:215], v188 offset:55296
	ds_read_b128 v[216:219], v188 offset:56320
	global_load_lds_dwordx4 v[182:183], off
	s_add_i32 m0, s40, 0x2000
	s_add_u32 s38, s38, 0x80080
	v_lshl_add_u64 v[182:183], v[220:221], 0, s[14:15]
	s_addc_u32 s39, s39, 0
	s_add_i32 s40, s58, s35
	global_load_lds_dwordx4 v[182:183], off
	v_lshl_add_u64 v[182:183], s[38:39], 0, v[148:149]
	s_mov_b32 m0, s40
	s_nop 0
	global_load_lds_dwordx4 v[182:183], off
	v_lshl_add_u64 v[182:183], s[38:39], 0, v[144:145]
	s_add_i32 m0, s40, 0x2000
	s_nop 0
	global_load_lds_dwordx4 v[182:183], off
	v_lshl_add_u64 v[182:183], v[222:223], 0, s[14:15]
	s_mov_b32 m0, s49
	s_nop 0
	global_load_lds_dwordx4 v[182:183], off
	v_lshl_add_u64 v[182:183], v[224:225], 0, s[14:15]
	s_mov_b32 m0, s50
	s_nop 0
	global_load_lds_dwordx4 v[182:183], off
	s_waitcnt vmcnt(8)
	s_waitcnt lgkmcnt(0)
	s_barrier
	s_setprio 1
	s_waitcnt lgkmcnt(0)
	v_mfma_f32_16x16x32_bf16 v[60:63], v[128:131], v[178:181], v[60:63]
	v_mfma_f32_16x16x32_bf16 v[56:59], v[136:139], v[178:181], v[56:59]
	v_mfma_f32_16x16x32_bf16 v[44:47], v[128:131], v[196:199], v[44:47]
	v_mfma_f32_16x16x32_bf16 v[40:43], v[136:139], v[196:199], v[40:43]
	v_mfma_f32_16x16x32_bf16 v[28:31], v[128:131], v[204:207], v[28:31]
	v_mfma_f32_16x16x32_bf16 v[24:27], v[136:139], v[204:207], v[24:27]
	v_mfma_f32_16x16x32_bf16 v[12:15], v[128:131], v[212:215], v[12:15]
	v_mfma_f32_16x16x32_bf16 v[8:11], v[136:139], v[212:215], v[8:11]
	v_mfma_f32_16x16x32_bf16 v[60:63], v[132:135], v[192:195], v[60:63]
	v_mfma_f32_16x16x32_bf16 v[56:59], v[140:143], v[192:195], v[56:59]
	v_mfma_f32_16x16x32_bf16 v[44:47], v[132:135], v[200:203], v[44:47]
	v_mfma_f32_16x16x32_bf16 v[40:43], v[140:143], v[200:203], v[40:43]
	v_mfma_f32_16x16x32_bf16 v[28:31], v[132:135], v[208:211], v[28:31]
	v_mfma_f32_16x16x32_bf16 v[24:27], v[140:143], v[208:211], v[24:27]
	v_mfma_f32_16x16x32_bf16 v[12:15], v[132:135], v[216:219], v[12:15]
	v_mfma_f32_16x16x32_bf16 v[8:11], v[140:143], v[216:219], v[8:11]
	s_setprio 0
	s_setprio 1
	v_mfma_f32_16x16x32_bf16 v[52:55], v[162:165], v[178:181], v[52:55]
	v_mfma_f32_16x16x32_bf16 v[48:51], v[170:173], v[178:181], v[48:51]
	v_mfma_f32_16x16x32_bf16 v[36:39], v[162:165], v[196:199], v[36:39]
	v_mfma_f32_16x16x32_bf16 v[32:35], v[170:173], v[196:199], v[32:35]
	v_mfma_f32_16x16x32_bf16 v[20:23], v[162:165], v[204:207], v[20:23]
	v_mfma_f32_16x16x32_bf16 v[16:19], v[170:173], v[204:207], v[16:19]
	v_mfma_f32_16x16x32_bf16 v[4:7], v[162:165], v[212:215], v[4:7]
	v_mfma_f32_16x16x32_bf16 v[0:3], v[170:173], v[212:215], v[0:3]
	v_mfma_f32_16x16x32_bf16 v[52:55], v[166:169], v[192:195], v[52:55]
	v_mfma_f32_16x16x32_bf16 v[48:51], v[174:177], v[192:195], v[48:51]
	v_mfma_f32_16x16x32_bf16 v[36:39], v[166:169], v[200:203], v[36:39]
	v_mfma_f32_16x16x32_bf16 v[32:35], v[174:177], v[200:203], v[32:35]
	v_mfma_f32_16x16x32_bf16 v[20:23], v[166:169], v[208:211], v[20:23]
	v_mfma_f32_16x16x32_bf16 v[16:19], v[174:177], v[208:211], v[16:19]
	v_mfma_f32_16x16x32_bf16 v[4:7], v[166:169], v[216:219], v[4:7]
	v_mfma_f32_16x16x32_bf16 v[0:3], v[174:177], v[216:219], v[0:3]
	s_setprio 0
	s_barrier
	s_add_i32 s56, s56, 2
	s_add_u32 s6, s6, 0x100
	s_addc_u32 s7, s7, 0
	s_add_u32 s5, s5, 0x100
	s_addc_u32 s25, s25, 0
	s_cmp_gt_u32 s56, 29
	s_cbranch_scc0 .LBB0_672
	s_and_b64 vcc, exec, s[18:19]
	s_cbranch_vccz .LBB0_675
	s_barrier
